# stacked: SGPR compaction offset + fused floor-convert in select_rows on top of DPP scans/LayerNorm reductions
# speedup vs baseline: 1.0103x; 1.0010x over previous
; #define LAS __attribute__((address_space(3)))
; #define GAS __attribute__((address_space(1)))
; __device__ __forceinline__ unsigned skey_of(float f) { const unsigned u = __float_as_uint(f); return u ^ ((unsigned)((int)u >> 31) | 0x80000000u); }
; template <int NJ>
; __device__ __forceinline__ void select_rows(const GAS float* sr0, GAS unsigned long long* mb0, LAS unsigned* hist, LAS unsigned* kbuf, int ntl, int lane) {
;     ...
;     for (int rr = 0; rr < 8; ++rr) {
;         const GAS float* srow = sr0 + (size_t)rr * SEQ;
;         float fv[NJ];
; #pragma unroll
;         for (int j = 0; j < NJ; ++j) fv[j] = srow[64 * j];
;         { unsigned z = 0u; asm volatile("" : "+v"(z));
;           *(LAS u32x4*)(hist + 4 * lane) = (u32x4){z, z, z, z}; if (lane < 2) hist[256 + lane] = z; }
;         __builtin_amdgcn_wave_barrier();
;         unsigned key[NJ];
; #pragma unroll
;         for (int j = 0; j < NJ; ++j) {
;             const float f = fv[j]; const bool ok = (vm >> j) & 1u;
;             key[j] = ok ? skey_of(f) : 0u;
;             const int bk = min(max((int)floorf(f + f) + 128, 0), 255);
;             __hip_atomic_fetch_add(hist + (ok ? bk : 256), 1u, __ATOMIC_RELAXED, __HIP_MEMORY_SCOPE_WORKGROUP);
;         }
.LBB0_382:
	s_mov_b32 s100, 0
	s_lshl_b32 s88, s12, 11
	v_lshl_add_u64 v[2:3], s[88:89], 2, v[8:9]
	s_movk_i32 s0, 0x1000
	s_add_i32 s98, s88, 0x800
	s_mov_b32 s99, s89
	s_waitcnt vmcnt(1)
	v_mov_b32_e32 v45, v51
	v_mov_b32_e32 v10, v52
	v_mov_b32_e32 v11, v53
	v_mov_b32_e32 v12, v54
	v_mov_b32_e32 v13, v55
	v_mov_b32_e32 v14, v56
	v_mov_b32_e32 v15, v57
	v_mov_b32_e32 v16, v58
	v_mov_b32_e32 v17, v59
	v_mov_b32_e32 v18, v60
	v_mov_b32_e32 v19, v61
	v_mov_b32_e32 v20, v62
	v_mov_b32_e32 v21, v63
	v_mov_b32_e32 v22, v64
	v_mov_b32_e32 v23, v65
	v_mov_b32_e32 v24, v66
	v_mov_b32_e32 v25, v67
	v_mov_b32_e32 v26, v68
	v_mov_b32_e32 v27, v69
	v_mov_b32_e32 v28, v70
	v_mov_b32_e32 v29, v71
	v_mov_b32_e32 v30, v72
	v_mov_b32_e32 v31, v73
	v_mov_b32_e32 v32, v74
	v_mov_b32_e32 v33, v75
	v_mov_b32_e32 v34, v76
	v_mov_b32_e32 v35, v77
	v_mov_b32_e32 v36, v78
	v_mov_b32_e32 v37, v79
	v_mov_b32_e32 v42, v80
	v_mov_b32_e32 v43, v81
	v_mov_b32_e32 v44, v82
	v_lshl_add_u64 v[84:85], s[98:99], 2, v[8:9]
	v_add_co_u32_e32 v86, vcc, 0x1000, v84
	s_nop 1
	v_addc_co_u32_e32 v87, vcc, 0, v85, vcc
	global_load_dword v51, v[84:85], off
	global_load_dword v52, v[84:85], off offset:256
	global_load_dword v53, v[84:85], off offset:512
	global_load_dword v54, v[84:85], off offset:768
	global_load_dword v55, v[84:85], off offset:1024
	global_load_dword v56, v[84:85], off offset:1280
	global_load_dword v57, v[84:85], off offset:1536
	global_load_dword v58, v[84:85], off offset:1792
	global_load_dword v59, v[84:85], off offset:2048
	global_load_dword v60, v[84:85], off offset:2304
	global_load_dword v61, v[84:85], off offset:2560
	global_load_dword v62, v[84:85], off offset:2816
	global_load_dword v63, v[84:85], off offset:3072
	global_load_dword v64, v[84:85], off offset:3328
	global_load_dword v65, v[84:85], off offset:3584
	global_load_dword v66, v[84:85], off offset:3840
	global_load_dword v67, v[86:87], off
	global_load_dword v68, v[86:87], off offset:256
	global_load_dword v69, v[86:87], off offset:512
	global_load_dword v70, v[86:87], off offset:768
	global_load_dword v71, v[86:87], off offset:1024
	global_load_dword v72, v[86:87], off offset:1280
	global_load_dword v73, v[86:87], off offset:1536
	global_load_dword v74, v[86:87], off offset:1792
	global_load_dword v75, v[86:87], off offset:2048
	global_load_dword v76, v[86:87], off offset:2304
	global_load_dword v77, v[86:87], off offset:2560
	global_load_dword v78, v[86:87], off offset:2816
	global_load_dword v79, v[86:87], off offset:3072
	global_load_dword v80, v[86:87], off offset:3328
	global_load_dword v81, v[86:87], off offset:3584
	global_load_dword v82, v[86:87], off offset:3840
	v_mov_b32_e32 v2, 0
	s_nop 0
	v_mov_b32_e32 v3, v2
	v_mov_b32_e32 v4, v2
	v_mov_b32_e32 v5, v2
	ds_write_b128 v7, v[2:5]
	s_and_saveexec_b64 s[0:1], s[74:75]
	v_add_u32_e32 v3, v7, v38
	ds_write_b32 v3, v2 offset:1024
	s_or_b64 exec, exec, s[0:1]
	v_add_f32_e32 v2, v45, v45
	v_cvt_flr_i32_f32_e32 v2, v2
	v_add_f32_e32 v3, v10, v10
	v_cvt_flr_i32_f32_e32 v3, v3
	v_max_i32_e32 v2, 0xffffff80, v2
	v_add_u32_e32 v2, 0x80, v2
	v_min_u32_e32 v2, 0xff, v2
	v_cndmask_b32_e64 v2, v2, v226, s[94:95]
	v_lshl_add_u32 v2, v2, 2, s6
	ds_add_u32 v2, v223
	v_max_i32_e32 v2, 0xffffff80, v3
	v_add_f32_e32 v3, v11, v11
	v_add_u32_e32 v2, 0x80, v2
	v_cvt_flr_i32_f32_e32 v3, v3
	v_min_u32_e32 v2, 0xff, v2
	v_cndmask_b32_e64 v2, v2, v226, s[14:15]
	v_lshl_add_u32 v2, v2, 2, s6
	ds_add_u32 v2, v223
	v_max_i32_e32 v2, 0xffffff80, v3
	v_add_f32_e32 v3, v12, v12
	v_add_u32_e32 v2, 0x80, v2
	v_cvt_flr_i32_f32_e32 v3, v3
	v_min_u32_e32 v2, 0xff, v2
	v_cndmask_b32_e64 v2, v2, v226, s[16:17]
	v_lshl_add_u32 v2, v2, 2, s6
	ds_add_u32 v2, v223
	v_max_i32_e32 v2, 0xffffff80, v3
	v_add_f32_e32 v3, v13, v13
	v_add_u32_e32 v2, 0x80, v2
	v_cvt_flr_i32_f32_e32 v3, v3
	v_min_u32_e32 v2, 0xff, v2
	v_cndmask_b32_e64 v2, v2, v226, s[18:19]
	v_lshl_add_u32 v2, v2, 2, s6
	ds_add_u32 v2, v223
	v_max_i32_e32 v2, 0xffffff80, v3
	v_add_f32_e32 v3, v14, v14
	v_add_u32_e32 v2, 0x80, v2
	v_cvt_flr_i32_f32_e32 v3, v3
	v_min_u32_e32 v2, 0xff, v2
	v_cndmask_b32_e64 v2, v2, v226, s[24:25]
	v_lshl_add_u32 v2, v2, 2, s6
	ds_add_u32 v2, v223
	v_max_i32_e32 v2, 0xffffff80, v3
	v_add_f32_e32 v3, v15, v15
	v_add_u32_e32 v2, 0x80, v2
	v_cvt_flr_i32_f32_e32 v3, v3
	v_min_u32_e32 v2, 0xff, v2
	v_cndmask_b32_e64 v2, v2, v226, s[26:27]
	v_lshl_add_u32 v2, v2, 2, s6
	ds_add_u32 v2, v223
	v_max_i32_e32 v2, 0xffffff80, v3
	v_add_f32_e32 v3, v16, v16
	v_add_u32_e32 v2, 0x80, v2
	v_cvt_flr_i32_f32_e32 v3, v3
	v_min_u32_e32 v2, 0xff, v2
	v_cndmask_b32_e64 v2, v2, v226, s[28:29]
	v_lshl_add_u32 v2, v2, 2, s6
	ds_add_u32 v2, v223
	v_max_i32_e32 v2, 0xffffff80, v3
	v_add_f32_e32 v3, v17, v17
	v_add_u32_e32 v2, 0x80, v2
	v_cvt_flr_i32_f32_e32 v3, v3
	v_min_u32_e32 v2, 0xff, v2
	v_cndmask_b32_e64 v2, v2, v226, s[30:31]
	v_lshl_add_u32 v2, v2, 2, s6
	ds_add_u32 v2, v223
	v_max_i32_e32 v2, 0xffffff80, v3
	v_add_f32_e32 v3, v18, v18
	v_add_u32_e32 v2, 0x80, v2
	v_cvt_flr_i32_f32_e32 v3, v3
	v_min_u32_e32 v2, 0xff, v2
	v_cndmask_b32_e64 v2, v2, v226, s[34:35]
	v_lshl_add_u32 v2, v2, 2, s6
	ds_add_u32 v2, v223
	v_max_i32_e32 v2, 0xffffff80, v3
	v_add_f32_e32 v3, v19, v19
	v_add_u32_e32 v2, 0x80, v2
	v_cvt_flr_i32_f32_e32 v3, v3
	v_min_u32_e32 v2, 0xff, v2
	v_cndmask_b32_e64 v2, v2, v226, s[36:37]
	v_lshl_add_u32 v2, v2, 2, s6
	ds_add_u32 v2, v223
	v_max_i32_e32 v2, 0xffffff80, v3
	v_add_f32_e32 v3, v20, v20
	v_add_u32_e32 v2, 0x80, v2
	v_cvt_flr_i32_f32_e32 v3, v3
	v_min_u32_e32 v2, 0xff, v2
	v_cndmask_b32_e64 v2, v2, v226, s[38:39]
	v_lshl_add_u32 v2, v2, 2, s6
	ds_add_u32 v2, v223
	v_max_i32_e32 v2, 0xffffff80, v3
; #define LAS __attribute__((address_space(3)))
; __device__ __forceinline__ unsigned skey_of(float f) { const unsigned u = __float_as_uint(f); return u ^ ((unsigned)((int)u >> 31) | 0x80000000u); }
; template <int NJ>
; __device__ __forceinline__ void select_rows(const GAS float* sr0, GAS unsigned long long* mb0, LAS unsigned* hist, LAS unsigned* kbuf, int ntl, int lane) {
;     ...
;         for (int j = 0; j < NJ; ++j) {
;             const float f = fv[j]; const bool ok = (vm >> j) & 1u;
;             key[j] = ok ? skey_of(f) : 0u;
;             const int bk = min(max((int)floorf(f + f) + 128, 0), 255);
;             __hip_atomic_fetch_add(hist + (ok ? bk : 256), 1u, __ATOMIC_RELAXED, __HIP_MEMORY_SCOPE_WORKGROUP);
;         }
;         __builtin_amdgcn_wave_barrier();
;         asm volatile("s_waitcnt lgkmcnt(0)" ::: "memory");
;         unsigned B, rem, C;
;         {
;             const u32x4 hv = *(const LAS u32x4*)(hist + 4 * lane);
;             const unsigned s4 = hv.x + hv.y + hv.z + hv.w;
;             unsigned S = s4;
; #pragma unroll
;             for (int off = 1; off < 64; off <<= 1) { const unsigned n = __shfl_down(S, off); if (lane + off < 64) S += n; }
;             const unsigned excl = S - s4;
;             const bool mine = (excl < 256u) && (256u <= S);
;             unsigned dl, above, cnt, c = excl;
;             if (c + hv.w >= 256u) { dl = 3; above = c; cnt = hv.w; } else { c += hv.w; if (c + hv.z >= 256u) { dl = 2; above = c; cnt = hv.z; } else { c += hv.z; if (c + hv.y >= 256u) { dl = 1; above = c; cnt = hv.y; } else { c += hv.y; dl = 0; above = c; cnt = hv.x; } } }
	v_add_f32_e32 v3, v21, v21
	v_add_u32_e32 v2, 0x80, v2
	v_cvt_flr_i32_f32_e32 v3, v3
	v_min_u32_e32 v2, 0xff, v2
	v_cndmask_b32_e64 v2, v2, v226, s[40:41]
	v_lshl_add_u32 v2, v2, 2, s6
	ds_add_u32 v2, v223
	v_max_i32_e32 v2, 0xffffff80, v3
	v_add_f32_e32 v3, v22, v22
	v_add_u32_e32 v2, 0x80, v2
	v_cvt_flr_i32_f32_e32 v3, v3
	v_min_u32_e32 v2, 0xff, v2
	v_cndmask_b32_e64 v2, v2, v226, s[42:43]
	v_lshl_add_u32 v2, v2, 2, s6
	ds_add_u32 v2, v223
	v_max_i32_e32 v2, 0xffffff80, v3
	v_add_f32_e32 v3, v23, v23
	v_add_u32_e32 v2, 0x80, v2
	v_cvt_flr_i32_f32_e32 v3, v3
	v_min_u32_e32 v2, 0xff, v2
	v_cndmask_b32_e64 v2, v2, v226, s[44:45]
	v_lshl_add_u32 v2, v2, 2, s6
	ds_add_u32 v2, v223
	v_max_i32_e32 v2, 0xffffff80, v3
	v_add_f32_e32 v3, v24, v24
	v_add_u32_e32 v2, 0x80, v2
	v_cvt_flr_i32_f32_e32 v3, v3
	v_min_u32_e32 v2, 0xff, v2
	v_cndmask_b32_e64 v2, v2, v226, s[46:47]
	v_lshl_add_u32 v2, v2, 2, s6
	ds_add_u32 v2, v223
	v_max_i32_e32 v2, 0xffffff80, v3
	v_add_f32_e32 v3, v25, v25
	v_add_u32_e32 v2, 0x80, v2
	v_cvt_flr_i32_f32_e32 v3, v3
	v_min_u32_e32 v2, 0xff, v2
	v_cndmask_b32_e64 v2, v2, v226, s[48:49]
	v_lshl_add_u32 v2, v2, 2, s6
	ds_add_u32 v2, v223
	v_max_i32_e32 v2, 0xffffff80, v3
	v_add_f32_e32 v3, v26, v26
	v_add_u32_e32 v2, 0x80, v2
	v_cvt_flr_i32_f32_e32 v3, v3
	v_min_u32_e32 v2, 0xff, v2
	v_cndmask_b32_e64 v2, v2, v226, s[50:51]
	v_lshl_add_u32 v2, v2, 2, s6
	ds_add_u32 v2, v223
	v_max_i32_e32 v2, 0xffffff80, v3
	v_add_f32_e32 v3, v27, v27
	v_add_u32_e32 v2, 0x80, v2
	v_cvt_flr_i32_f32_e32 v3, v3
	v_min_u32_e32 v2, 0xff, v2
	v_cndmask_b32_e64 v2, v2, v226, s[52:53]
	v_lshl_add_u32 v2, v2, 2, s6
	ds_add_u32 v2, v223
	v_max_i32_e32 v2, 0xffffff80, v3
	v_add_f32_e32 v3, v28, v28
	v_add_u32_e32 v2, 0x80, v2
	v_cvt_flr_i32_f32_e32 v3, v3
	v_min_u32_e32 v2, 0xff, v2
	v_cndmask_b32_e64 v2, v2, v226, s[54:55]
	v_lshl_add_u32 v2, v2, 2, s6
	ds_add_u32 v2, v223
	v_max_i32_e32 v2, 0xffffff80, v3
	v_add_f32_e32 v3, v29, v29
	v_add_u32_e32 v2, 0x80, v2
	v_cvt_flr_i32_f32_e32 v3, v3
	v_min_u32_e32 v2, 0xff, v2
	v_cndmask_b32_e64 v2, v2, v226, s[64:65]
	v_lshl_add_u32 v2, v2, 2, s6
	ds_add_u32 v2, v223
	v_max_i32_e32 v2, 0xffffff80, v3
	v_add_f32_e32 v3, v30, v30
	v_add_u32_e32 v2, 0x80, v2
	v_cvt_flr_i32_f32_e32 v3, v3
	v_min_u32_e32 v2, 0xff, v2
	v_cndmask_b32_e64 v2, v2, v226, s[66:67]
	v_lshl_add_u32 v2, v2, 2, s6
	ds_add_u32 v2, v223
	v_max_i32_e32 v2, 0xffffff80, v3
	v_add_f32_e32 v3, v31, v31
	v_add_u32_e32 v2, 0x80, v2
	v_cvt_flr_i32_f32_e32 v3, v3
	v_min_u32_e32 v2, 0xff, v2
	v_cndmask_b32_e64 v2, v2, v226, s[70:71]
	v_lshl_add_u32 v2, v2, 2, s6
	ds_add_u32 v2, v223
	v_max_i32_e32 v2, 0xffffff80, v3
	v_add_f32_e32 v3, v32, v32
	v_add_u32_e32 v2, 0x80, v2
	v_cvt_flr_i32_f32_e32 v3, v3
	v_min_u32_e32 v2, 0xff, v2
	v_cndmask_b32_e64 v2, v2, v226, s[72:73]
	v_lshl_add_u32 v2, v2, 2, s6
	ds_add_u32 v2, v223
	v_max_i32_e32 v2, 0xffffff80, v3
	v_add_f32_e32 v3, v33, v33
	v_add_u32_e32 v2, 0x80, v2
	v_cvt_flr_i32_f32_e32 v3, v3
	v_min_u32_e32 v2, 0xff, v2
	v_cndmask_b32_e64 v2, v2, v226, s[76:77]
	v_lshl_add_u32 v2, v2, 2, s6
	ds_add_u32 v2, v223
	v_max_i32_e32 v2, 0xffffff80, v3
	v_add_f32_e32 v3, v34, v34
	v_add_u32_e32 v2, 0x80, v2
	v_cvt_flr_i32_f32_e32 v3, v3
	v_min_u32_e32 v2, 0xff, v2
	v_cndmask_b32_e64 v2, v2, v226, s[78:79]
	v_lshl_add_u32 v2, v2, 2, s6
	ds_add_u32 v2, v223
	v_max_i32_e32 v2, 0xffffff80, v3
	v_add_f32_e32 v3, v35, v35
	v_add_u32_e32 v2, 0x80, v2
	v_cvt_flr_i32_f32_e32 v3, v3
	v_min_u32_e32 v2, 0xff, v2
	v_cndmask_b32_e64 v2, v2, v226, s[84:85]
	v_lshl_add_u32 v2, v2, 2, s6
	ds_add_u32 v2, v223
	v_max_i32_e32 v2, 0xffffff80, v3
	v_add_f32_e32 v3, v36, v36
	v_add_u32_e32 v2, 0x80, v2
	v_cvt_flr_i32_f32_e32 v3, v3
	v_min_u32_e32 v2, 0xff, v2
	v_cndmask_b32_e64 v2, v2, v226, s[90:91]
	v_lshl_add_u32 v2, v2, 2, s6
	ds_add_u32 v2, v223
	v_max_i32_e32 v2, 0xffffff80, v3
	v_add_f32_e32 v3, v37, v37
	v_add_u32_e32 v2, 0x80, v2
	v_cvt_flr_i32_f32_e32 v3, v3
	v_min_u32_e32 v2, 0xff, v2
	v_cndmask_b32_e64 v2, v2, v226, s[92:93]
	v_lshl_add_u32 v2, v2, 2, s6
	ds_add_u32 v2, v223
	v_max_i32_e32 v2, 0xffffff80, v3
	v_add_f32_e32 v3, v42, v42
	v_add_u32_e32 v2, 0x80, v2
	v_cvt_flr_i32_f32_e32 v3, v3
	v_min_u32_e32 v2, 0xff, v2
	v_cndmask_b32_e64 v2, v2, v226, s[8:9]
	v_lshl_add_u32 v2, v2, 2, s6
	ds_add_u32 v2, v223
	v_max_i32_e32 v2, 0xffffff80, v3
	v_add_f32_e32 v3, v43, v43
	v_add_u32_e32 v2, 0x80, v2
	v_cvt_flr_i32_f32_e32 v3, v3
	v_readlane_b32 s0, v254, 33
	v_min_u32_e32 v2, 0xff, v2
	v_readlane_b32 s1, v254, 34
	s_nop 1
	v_cndmask_b32_e64 v2, v2, v226, s[0:1]
	v_lshl_add_u32 v2, v2, 2, s6
	ds_add_u32 v2, v223
	v_max_i32_e32 v2, 0xffffff80, v3
	v_add_f32_e32 v3, v44, v44
	v_add_u32_e32 v2, 0x80, v2
	v_cvt_flr_i32_f32_e32 v3, v3
	v_readlane_b32 s0, v254, 35
	v_min_u32_e32 v2, 0xff, v2
	v_readlane_b32 s1, v254, 36
	s_nop 1
	v_cndmask_b32_e64 v2, v2, v226, s[0:1]
	v_lshl_add_u32 v2, v2, 2, s6
	ds_add_u32 v2, v223
	v_max_i32_e32 v2, 0xffffff80, v3
	v_add_u32_e32 v2, 0x80, v2
	v_readlane_b32 s0, v254, 37
	v_min_u32_e32 v2, 0xff, v2
	v_readlane_b32 s1, v254, 38
	s_nop 1
	v_cndmask_b32_e64 v2, v2, v226, s[0:1]
	v_lshl_add_u32 v2, v2, 2, s6
	ds_add_u32 v2, v223
	s_waitcnt lgkmcnt(0)
	ds_read_b128 v[2:5], v7
	v_readlane_b32 s0, v254, 41
	v_readlane_b32 s1, v254, 42
	s_waitcnt lgkmcnt(0)
	v_add_u32_e32 v46, v2, v3
	v_add3_u32 v47, v46, v4, v5
	v_mov_b32_e32 v46, v47
	s_nop 1
	v_add_u32_dpp v46, v46, v46 row_shr:1 row_mask:0xf bank_mask:0xf bound_ctrl:0
	s_nop 1
	v_add_u32_dpp v46, v46, v46 row_shr:2 row_mask:0xf bank_mask:0xf bound_ctrl:0
	s_nop 1
	v_add_u32_dpp v46, v46, v46 row_shr:4 row_mask:0xf bank_mask:0xf bound_ctrl:0
	s_nop 1
	v_add_u32_dpp v46, v46, v46 row_shr:8 row_mask:0xf bank_mask:0xf bound_ctrl:0
	s_nop 1
	v_add_u32_dpp v46, v46, v46 row_bcast:15 row_mask:0xa bank_mask:0xf
	s_nop 1
	v_add_u32_dpp v46, v46, v46 row_bcast:31 row_mask:0xc bank_mask:0xf
	s_nop 1
	v_readlane_b32 s0, v46, 63
	s_nop 1
	v_sub_u32_e32 v48, s0, v46
	v_add_u32_e32 v46, v48, v47
	v_mov_b32_e32 v47, v48
	v_add_u32_e32 v50, v47, v5
	v_cmp_gt_u32_e32 vcc, s63, v50
	v_mov_b32_e32 v48, 3
	v_mov_b32_e32 v49, v47
	s_and_saveexec_b64 s[0:1], vcc
	s_cbranch_execz .LBB0_388
	v_add_u32_e32 v5, v50, v4
	v_cmp_gt_u32_e32 vcc, s63, v5
	v_mov_b32_e32 v48, 2
	s_and_saveexec_b64 s[2:3], vcc
	v_add_u32_e32 v4, v5, v3
	s_movk_i32 s4, 0xff
	v_cmp_lt_u32_e32 vcc, s4, v4
	s_nop 1
	v_cndmask_b32_e64 v48, 0, 1, vcc
	v_cndmask_b32_e32 v50, v4, v5, vcc
	v_cndmask_b32_e32 v4, v2, v3, vcc
	s_or_b64 exec, exec, s[2:3]
	v_mov_b32_e32 v5, v4
	v_mov_b32_e32 v49, v50

; #define LAS __attribute__((address_space(3)))
; #define GAS __attribute__((address_space(1)))
; __device__ __forceinline__ unsigned skey_of(float f) { const unsigned u = __float_as_uint(f); return u ^ ((unsigned)((int)u >> 31) | 0x80000000u); }
; template <int NJ>
; __device__ __forceinline__ void select_rows(const GAS float* sr0, GAS unsigned long long* mb0, LAS unsigned* hist, LAS unsigned* kbuf, int ntl, int lane) {
;     ...
;     for (int rr = 0; rr < 8; ++rr) {
;         const GAS float* srow = sr0 + (size_t)rr * SEQ;
;         float fv[NJ];
; #pragma unroll
;         for (int j = 0; j < NJ; ++j) fv[j] = srow[64 * j];
;         { unsigned z = 0u; asm volatile("" : "+v"(z));
;           *(LAS u32x4*)(hist + 4 * lane) = (u32x4){z, z, z, z}; if (lane < 2) hist[256 + lane] = z; }
;         __builtin_amdgcn_wave_barrier();
;         unsigned key[NJ];
; #pragma unroll
;         for (int j = 0; j < NJ; ++j) {
;             const float f = fv[j]; const bool ok = (vm >> j) & 1u;
;             key[j] = ok ? skey_of(f) : 0u;
;             const int bk = min(max((int)floorf(f + f) + 128, 0), 255);
;             __hip_atomic_fetch_add(hist + (ok ? bk : 256), 1u, __ATOMIC_RELAXED, __HIP_MEMORY_SCOPE_WORKGROUP);
;         }
.LBB0_533:
	s_mov_b32 s100, 0
	s_lshl_b32 s88, s7, 11
	v_lshl_add_u64 v[2:3], s[88:89], 2, v[8:9]
	global_load_dword v33, v[2:3], off
	global_load_dword v10, v[2:3], off offset:256
	global_load_dword v11, v[2:3], off offset:512
	global_load_dword v12, v[2:3], off offset:768
	global_load_dword v13, v[2:3], off offset:1024
	global_load_dword v14, v[2:3], off offset:1280
	global_load_dword v15, v[2:3], off offset:1536
	global_load_dword v16, v[2:3], off offset:1792
	global_load_dword v17, v[2:3], off offset:2048
	global_load_dword v18, v[2:3], off offset:2304
	global_load_dword v19, v[2:3], off offset:2560
	global_load_dword v20, v[2:3], off offset:2816
	global_load_dword v21, v[2:3], off offset:3072
	global_load_dword v22, v[2:3], off offset:3328
	global_load_dword v23, v[2:3], off offset:3584
	global_load_dword v24, v[2:3], off offset:3840
	s_movk_i32 s0, 0x1000
	v_add_co_u32_e32 v2, vcc, s0, v2
	s_nop 1
	v_addc_co_u32_e32 v3, vcc, 0, v3, vcc
	global_load_dword v25, v[2:3], off
	global_load_dword v26, v[2:3], off offset:256
	global_load_dword v27, v[2:3], off offset:512
	global_load_dword v28, v[2:3], off offset:768
	global_load_dword v29, v[2:3], off offset:1024
	global_load_dword v30, v[2:3], off offset:1280
	global_load_dword v31, v[2:3], off offset:1536
	global_load_dword v32, v[2:3], off offset:1792
	v_mov_b32_e32 v2, 0
	s_nop 0
	v_mov_b32_e32 v3, v2
	v_mov_b32_e32 v4, v2
	v_mov_b32_e32 v5, v2
	ds_write_b128 v7, v[2:5]
	s_and_saveexec_b64 s[0:1], s[74:75]
	v_add_u32_e32 v3, v7, v38
	ds_write_b32 v3, v2 offset:1024
	s_or_b64 exec, exec, s[0:1]
	s_waitcnt vmcnt(23)
	v_add_f32_e32 v2, v33, v33
	v_cvt_flr_i32_f32_e32 v2, v2
	s_waitcnt vmcnt(22)
	v_add_f32_e32 v3, v10, v10
	v_cvt_flr_i32_f32_e32 v3, v3
	v_max_i32_e32 v2, 0xffffff80, v2
	v_add_u32_e32 v2, 0x80, v2
	v_min_u32_e32 v2, 0xff, v2
	v_cndmask_b32_e64 v2, v2, v226, s[14:15]
	v_lshl_add_u32 v2, v2, 2, s6
	ds_add_u32 v2, v223
	v_max_i32_e32 v2, 0xffffff80, v3
	s_waitcnt vmcnt(21)
	v_add_f32_e32 v3, v11, v11
	v_add_u32_e32 v2, 0x80, v2
	v_cvt_flr_i32_f32_e32 v3, v3
	v_min_u32_e32 v2, 0xff, v2
	v_cndmask_b32_e64 v2, v2, v226, s[16:17]
	v_lshl_add_u32 v2, v2, 2, s6
	ds_add_u32 v2, v223
	v_max_i32_e32 v2, 0xffffff80, v3
	s_waitcnt vmcnt(20)
	v_add_f32_e32 v3, v12, v12
	v_add_u32_e32 v2, 0x80, v2
	v_cvt_flr_i32_f32_e32 v3, v3
	v_min_u32_e32 v2, 0xff, v2
	v_cndmask_b32_e64 v2, v2, v226, s[18:19]
	v_lshl_add_u32 v2, v2, 2, s6
	ds_add_u32 v2, v223
	v_max_i32_e32 v2, 0xffffff80, v3
	s_waitcnt vmcnt(19)
	v_add_f32_e32 v3, v13, v13
	v_add_u32_e32 v2, 0x80, v2
	v_cvt_flr_i32_f32_e32 v3, v3
	v_min_u32_e32 v2, 0xff, v2
	v_cndmask_b32_e64 v2, v2, v226, s[4:5]
	v_lshl_add_u32 v2, v2, 2, s6
	ds_add_u32 v2, v223
	v_max_i32_e32 v2, 0xffffff80, v3
	s_waitcnt vmcnt(18)
	v_add_f32_e32 v3, v14, v14
	v_add_u32_e32 v2, 0x80, v2
	v_cvt_flr_i32_f32_e32 v3, v3
	v_min_u32_e32 v2, 0xff, v2
	v_cndmask_b32_e64 v2, v2, v226, s[10:11]
	v_lshl_add_u32 v2, v2, 2, s6
	ds_add_u32 v2, v223
	v_max_i32_e32 v2, 0xffffff80, v3
	s_waitcnt vmcnt(17)
	v_add_f32_e32 v3, v15, v15
	v_add_u32_e32 v2, 0x80, v2
	v_cvt_flr_i32_f32_e32 v3, v3
	v_min_u32_e32 v2, 0xff, v2
	v_cndmask_b32_e64 v2, v2, v226, s[24:25]
	v_lshl_add_u32 v2, v2, 2, s6
	ds_add_u32 v2, v223
	v_max_i32_e32 v2, 0xffffff80, v3
	s_waitcnt vmcnt(16)
	v_add_f32_e32 v3, v16, v16
	v_add_u32_e32 v2, 0x80, v2
	v_cvt_flr_i32_f32_e32 v3, v3
	v_min_u32_e32 v2, 0xff, v2
	v_cndmask_b32_e64 v2, v2, v226, s[26:27]
	v_lshl_add_u32 v2, v2, 2, s6
	ds_add_u32 v2, v223
	v_max_i32_e32 v2, 0xffffff80, v3
	s_waitcnt vmcnt(15)
	v_add_f32_e32 v3, v17, v17
	v_add_u32_e32 v2, 0x80, v2
	v_cvt_flr_i32_f32_e32 v3, v3
	v_min_u32_e32 v2, 0xff, v2
	v_cndmask_b32_e64 v2, v2, v226, s[28:29]
	v_lshl_add_u32 v2, v2, 2, s6
	ds_add_u32 v2, v223
	v_max_i32_e32 v2, 0xffffff80, v3
	s_waitcnt vmcnt(14)
	v_add_f32_e32 v3, v18, v18
	v_add_u32_e32 v2, 0x80, v2
	v_cvt_flr_i32_f32_e32 v3, v3
	v_min_u32_e32 v2, 0xff, v2
	v_cndmask_b32_e64 v2, v2, v226, s[30:31]
	v_lshl_add_u32 v2, v2, 2, s6
	ds_add_u32 v2, v223
	v_max_i32_e32 v2, 0xffffff80, v3
	s_waitcnt vmcnt(13)
	v_add_f32_e32 v3, v19, v19
	v_add_u32_e32 v2, 0x80, v2
	v_cvt_flr_i32_f32_e32 v3, v3
	v_min_u32_e32 v2, 0xff, v2
	v_cndmask_b32_e64 v2, v2, v226, s[34:35]
	v_lshl_add_u32 v2, v2, 2, s6
	ds_add_u32 v2, v223
	v_max_i32_e32 v2, 0xffffff80, v3
	s_waitcnt vmcnt(12)
	v_add_f32_e32 v3, v20, v20
	v_add_u32_e32 v2, 0x80, v2
	v_cvt_flr_i32_f32_e32 v3, v3
	v_min_u32_e32 v2, 0xff, v2
	v_cndmask_b32_e64 v2, v2, v226, s[36:37]
	v_lshl_add_u32 v2, v2, 2, s6
	ds_add_u32 v2, v223
	v_max_i32_e32 v2, 0xffffff80, v3
	s_waitcnt vmcnt(11)
; #define LAS __attribute__((address_space(3)))
; __device__ __forceinline__ unsigned skey_of(float f) { const unsigned u = __float_as_uint(f); return u ^ ((unsigned)((int)u >> 31) | 0x80000000u); }
; template <int NJ>
; __device__ __forceinline__ void select_rows(const GAS float* sr0, GAS unsigned long long* mb0, LAS unsigned* hist, LAS unsigned* kbuf, int ntl, int lane) {
;     ...
;         for (int j = 0; j < NJ; ++j) {
;             const float f = fv[j]; const bool ok = (vm >> j) & 1u;
;             key[j] = ok ? skey_of(f) : 0u;
;             const int bk = min(max((int)floorf(f + f) + 128, 0), 255);
;             __hip_atomic_fetch_add(hist + (ok ? bk : 256), 1u, __ATOMIC_RELAXED, __HIP_MEMORY_SCOPE_WORKGROUP);
;         }
;         __builtin_amdgcn_wave_barrier();
;         asm volatile("s_waitcnt lgkmcnt(0)" ::: "memory");
;         unsigned B, rem, C;
;         {
;             const u32x4 hv = *(const LAS u32x4*)(hist + 4 * lane);
;             const unsigned s4 = hv.x + hv.y + hv.z + hv.w;
;             unsigned S = s4;
; #pragma unroll
;             for (int off = 1; off < 64; off <<= 1) { const unsigned n = __shfl_down(S, off); if (lane + off < 64) S += n; }
;             const unsigned excl = S - s4;
;             const bool mine = (excl < 256u) && (256u <= S);
;             unsigned dl, above, cnt, c = excl;
;             if (c + hv.w >= 256u) { dl = 3; above = c; cnt = hv.w; } else { c += hv.w; if (c + hv.z >= 256u) { dl = 2; above = c; cnt = hv.z; } else { c += hv.z; if (c + hv.y >= 256u) { dl = 1; above = c; cnt = hv.y; } else { c += hv.y; dl = 0; above = c; cnt = hv.x; } } }
	v_add_f32_e32 v3, v21, v21
	v_add_u32_e32 v2, 0x80, v2
	v_cvt_flr_i32_f32_e32 v3, v3
	v_min_u32_e32 v2, 0xff, v2
	v_cndmask_b32_e64 v2, v2, v226, s[38:39]
	v_lshl_add_u32 v2, v2, 2, s6
	ds_add_u32 v2, v223
	v_max_i32_e32 v2, 0xffffff80, v3
	s_waitcnt vmcnt(10)
	v_add_f32_e32 v3, v22, v22
	v_add_u32_e32 v2, 0x80, v2
	v_cvt_flr_i32_f32_e32 v3, v3
	v_min_u32_e32 v2, 0xff, v2
	v_cndmask_b32_e64 v2, v2, v226, s[40:41]
	v_lshl_add_u32 v2, v2, 2, s6
	ds_add_u32 v2, v223
	v_max_i32_e32 v2, 0xffffff80, v3
	s_waitcnt vmcnt(9)
	v_add_f32_e32 v3, v23, v23
	v_add_u32_e32 v2, 0x80, v2
	v_cvt_flr_i32_f32_e32 v3, v3
	v_min_u32_e32 v2, 0xff, v2
	v_cndmask_b32_e64 v2, v2, v226, s[42:43]
	v_lshl_add_u32 v2, v2, 2, s6
	ds_add_u32 v2, v223
	v_max_i32_e32 v2, 0xffffff80, v3
	s_waitcnt vmcnt(8)
	v_add_f32_e32 v3, v24, v24
	v_add_u32_e32 v2, 0x80, v2
	v_cvt_flr_i32_f32_e32 v3, v3
	v_min_u32_e32 v2, 0xff, v2
	v_cndmask_b32_e64 v2, v2, v226, s[44:45]
	v_lshl_add_u32 v2, v2, 2, s6
	ds_add_u32 v2, v223
	v_max_i32_e32 v2, 0xffffff80, v3
	s_waitcnt vmcnt(7)
	v_add_f32_e32 v3, v25, v25
	v_add_u32_e32 v2, 0x80, v2
	v_cvt_flr_i32_f32_e32 v3, v3
	v_min_u32_e32 v2, 0xff, v2
	v_cndmask_b32_e64 v2, v2, v226, s[46:47]
	v_lshl_add_u32 v2, v2, 2, s6
	ds_add_u32 v2, v223
	v_max_i32_e32 v2, 0xffffff80, v3
	s_waitcnt vmcnt(6)
	v_add_f32_e32 v3, v26, v26
	v_add_u32_e32 v2, 0x80, v2
	v_cvt_flr_i32_f32_e32 v3, v3
	v_min_u32_e32 v2, 0xff, v2
	v_cndmask_b32_e64 v2, v2, v226, s[48:49]
	v_lshl_add_u32 v2, v2, 2, s6
	ds_add_u32 v2, v223
	v_max_i32_e32 v2, 0xffffff80, v3
	s_waitcnt vmcnt(5)
	v_add_f32_e32 v3, v27, v27
	v_add_u32_e32 v2, 0x80, v2
	v_cvt_flr_i32_f32_e32 v3, v3
	v_min_u32_e32 v2, 0xff, v2
	v_cndmask_b32_e64 v2, v2, v226, s[50:51]
	v_lshl_add_u32 v2, v2, 2, s6
	ds_add_u32 v2, v223
	v_max_i32_e32 v2, 0xffffff80, v3
	s_waitcnt vmcnt(4)
	v_add_f32_e32 v3, v28, v28
	v_add_u32_e32 v2, 0x80, v2
	v_cvt_flr_i32_f32_e32 v3, v3
	v_min_u32_e32 v2, 0xff, v2
	v_cndmask_b32_e64 v2, v2, v226, s[52:53]
	v_lshl_add_u32 v2, v2, 2, s6
	ds_add_u32 v2, v223
	v_max_i32_e32 v2, 0xffffff80, v3
	s_waitcnt vmcnt(3)
	v_add_f32_e32 v3, v29, v29
	v_add_u32_e32 v2, 0x80, v2
	v_cvt_flr_i32_f32_e32 v3, v3
	v_min_u32_e32 v2, 0xff, v2
	v_cndmask_b32_e64 v2, v2, v226, s[64:65]
	v_lshl_add_u32 v2, v2, 2, s6
	ds_add_u32 v2, v223
	v_max_i32_e32 v2, 0xffffff80, v3
	s_waitcnt vmcnt(2)
	v_add_f32_e32 v3, v30, v30
	v_add_u32_e32 v2, 0x80, v2
	v_cvt_flr_i32_f32_e32 v3, v3
	v_min_u32_e32 v2, 0xff, v2
	v_cndmask_b32_e64 v2, v2, v226, s[66:67]
	v_lshl_add_u32 v2, v2, 2, s6
	ds_add_u32 v2, v223
	v_max_i32_e32 v2, 0xffffff80, v3
	s_waitcnt vmcnt(1)
	v_add_f32_e32 v3, v31, v31
	v_add_u32_e32 v2, 0x80, v2
	v_cvt_flr_i32_f32_e32 v3, v3
	v_min_u32_e32 v2, 0xff, v2
	v_cndmask_b32_e64 v2, v2, v226, s[70:71]
	v_lshl_add_u32 v2, v2, 2, s6
	ds_add_u32 v2, v223
	v_max_i32_e32 v2, 0xffffff80, v3
	s_waitcnt vmcnt(0)
	v_add_f32_e32 v3, v32, v32
	v_add_u32_e32 v2, 0x80, v2
	v_cvt_flr_i32_f32_e32 v3, v3
	v_min_u32_e32 v2, 0xff, v2
	v_cndmask_b32_e64 v2, v2, v226, s[72:73]
	v_lshl_add_u32 v2, v2, 2, s6
	ds_add_u32 v2, v223
	v_max_i32_e32 v2, 0xffffff80, v3
	v_add_u32_e32 v2, 0x80, v2
	v_min_u32_e32 v2, 0xff, v2
	v_cndmask_b32_e64 v2, v2, v226, s[76:77]
	v_lshl_add_u32 v2, v2, 2, s6
	ds_add_u32 v2, v223
	s_waitcnt lgkmcnt(0)
	ds_read_b128 v[2:5], v7
	v_readlane_b32 s0, v254, 33
	v_readlane_b32 s1, v254, 34
	s_waitcnt lgkmcnt(0)
	v_add_u32_e32 v34, v2, v3
	v_add3_u32 v35, v34, v4, v5
	v_mov_b32_e32 v34, v35
	s_nop 1
	v_add_u32_dpp v34, v34, v34 row_shr:1 row_mask:0xf bank_mask:0xf bound_ctrl:0
	s_nop 1
	v_add_u32_dpp v34, v34, v34 row_shr:2 row_mask:0xf bank_mask:0xf bound_ctrl:0
	s_nop 1
	v_add_u32_dpp v34, v34, v34 row_shr:4 row_mask:0xf bank_mask:0xf bound_ctrl:0
	s_nop 1
	v_add_u32_dpp v34, v34, v34 row_shr:8 row_mask:0xf bank_mask:0xf bound_ctrl:0
	s_nop 1
	v_add_u32_dpp v34, v34, v34 row_bcast:15 row_mask:0xa bank_mask:0xf
	s_nop 1
	v_add_u32_dpp v34, v34, v34 row_bcast:31 row_mask:0xc bank_mask:0xf
	s_nop 1
	v_readlane_b32 s0, v34, 63
	s_nop 1
	v_sub_u32_e32 v36, s0, v34
	v_add_u32_e32 v34, v36, v35
	v_mov_b32_e32 v35, v36
	v_add_u32_e32 v42, v35, v5
	v_cmp_gt_u32_e32 vcc, s63, v42
	v_mov_b32_e32 v36, 3
	v_mov_b32_e32 v37, v35
	s_and_saveexec_b64 s[0:1], vcc
	s_cbranch_execz .LBB0_539
	v_add_u32_e32 v5, v42, v4
	v_cmp_gt_u32_e32 vcc, s63, v5
	v_mov_b32_e32 v36, 2
	s_and_saveexec_b64 s[2:3], vcc
	v_add_u32_e32 v4, v5, v3
	s_movk_i32 s8, 0xff
	v_cmp_lt_u32_e32 vcc, s8, v4
	s_nop 1
	v_cndmask_b32_e64 v36, 0, 1, vcc
	v_cndmask_b32_e32 v42, v4, v5, vcc
	v_cndmask_b32_e32 v4, v2, v3, vcc
	s_or_b64 exec, exec, s[2:3]
	v_mov_b32_e32 v5, v4
	v_mov_b32_e32 v37, v42

; #define LAS __attribute__((address_space(3)))
; #define GAS __attribute__((address_space(1)))
; __device__ __forceinline__ unsigned skey_of(float f) { const unsigned u = __float_as_uint(f); return u ^ ((unsigned)((int)u >> 31) | 0x80000000u); }
; template <int NJ>
; __device__ __forceinline__ void select_rows(const GAS float* sr0, GAS unsigned long long* mb0, LAS unsigned* hist, LAS unsigned* kbuf, int ntl, int lane) {
;     ...
;     for (int rr = 0; rr < 8; ++rr) {
;         const GAS float* srow = sr0 + (size_t)rr * SEQ;
;         float fv[NJ];
; #pragma unroll
;         for (int j = 0; j < NJ; ++j) fv[j] = srow[64 * j];
;         { unsigned z = 0u; asm volatile("" : "+v"(z));
;           *(LAS u32x4*)(hist + 4 * lane) = (u32x4){z, z, z, z}; if (lane < 2) hist[256 + lane] = z; }
;         __builtin_amdgcn_wave_barrier();
;         unsigned key[NJ];
; #pragma unroll
;         for (int j = 0; j < NJ; ++j) {
;             const float f = fv[j]; const bool ok = (vm >> j) & 1u;
;             key[j] = ok ? skey_of(f) : 0u;
;             const int bk = min(max((int)floorf(f + f) + 128, 0), 255);
;             __hip_atomic_fetch_add(hist + (ok ? bk : 256), 1u, __ATOMIC_RELAXED, __HIP_MEMORY_SCOPE_WORKGROUP);
;         }
;         __builtin_amdgcn_wave_barrier();
;         asm volatile("s_waitcnt lgkmcnt(0)" ::: "memory");
;         unsigned B, rem, C;
;         {
;             const u32x4 hv = *(const LAS u32x4*)(hist + 4 * lane);
;             const unsigned s4 = hv.x + hv.y + hv.z + hv.w;
;             unsigned S = s4;
; #pragma unroll
;             for (int off = 1; off < 64; off <<= 1) { const unsigned n = __shfl_down(S, off); if (lane + off < 64) S += n; }
;             const unsigned excl = S - s4;
;             const bool mine = (excl < 256u) && (256u <= S);
;             unsigned dl, above, cnt, c = excl;
;             if (c + hv.w >= 256u) { dl = 3; above = c; cnt = hv.w; } else { c += hv.w; if (c + hv.z >= 256u) { dl = 2; above = c; cnt = hv.z; } else { c += hv.z; if (c + hv.y >= 256u) { dl = 1; above = c; cnt = hv.y; } else { c += hv.y; dl = 0; above = c; cnt = hv.x; } } }
.LBB0_652:
	s_mov_b32 s100, 0
	s_lshl_b32 s88, s7, 11
	v_lshl_add_u64 v[2:3], s[88:89], 2, v[8:9]
	global_load_dword v25, v[2:3], off
	global_load_dword v10, v[2:3], off offset:256
	global_load_dword v11, v[2:3], off offset:512
	global_load_dword v12, v[2:3], off offset:768
	global_load_dword v13, v[2:3], off offset:1024
	global_load_dword v14, v[2:3], off offset:1280
	global_load_dword v15, v[2:3], off offset:1536
	global_load_dword v16, v[2:3], off offset:1792
	global_load_dword v17, v[2:3], off offset:2048
	global_load_dword v18, v[2:3], off offset:2304
	global_load_dword v19, v[2:3], off offset:2560
	global_load_dword v20, v[2:3], off offset:2816
	global_load_dword v21, v[2:3], off offset:3072
	global_load_dword v22, v[2:3], off offset:3328
	global_load_dword v23, v[2:3], off offset:3584
	global_load_dword v24, v[2:3], off offset:3840
	v_mov_b32_e32 v2, 0
	s_nop 0
	v_mov_b32_e32 v3, v2
	v_mov_b32_e32 v4, v2
	v_mov_b32_e32 v5, v2
	ds_write_b128 v7, v[2:5]
	s_mov_b64 s[8:9], exec
	v_readlane_b32 s38, v254, 15
	v_readlane_b32 s39, v254, 16
	s_and_b64 s[38:39], s[8:9], s[38:39]
	s_mov_b64 exec, s[38:39]
	v_add_u32_e32 v3, v7, v38
	ds_write_b32 v3, v2 offset:1024
	s_or_b64 exec, exec, s[8:9]
	s_waitcnt vmcnt(15)
	v_add_f32_e32 v2, v25, v25
	v_cvt_flr_i32_f32_e32 v2, v2
	s_waitcnt vmcnt(14)
	v_add_f32_e32 v3, v10, v10
	v_cvt_flr_i32_f32_e32 v3, v3
	v_max_i32_e32 v2, 0xffffff80, v2
	v_add_u32_e32 v2, 0x80, v2
	v_min_u32_e32 v2, 0xff, v2
	v_cndmask_b32_e64 v2, v2, v226, s[0:1]
	v_lshl_add_u32 v2, v2, 2, s6
	ds_add_u32 v2, v223
	v_max_i32_e32 v2, 0xffffff80, v3
	s_waitcnt vmcnt(13)
	v_add_f32_e32 v3, v11, v11
	v_add_u32_e32 v2, 0x80, v2
	v_cvt_flr_i32_f32_e32 v3, v3
	v_min_u32_e32 v2, 0xff, v2
	v_cndmask_b32_e64 v2, v2, v226, s[2:3]
	v_lshl_add_u32 v2, v2, 2, s6
	ds_add_u32 v2, v223
	v_max_i32_e32 v2, 0xffffff80, v3
	s_waitcnt vmcnt(12)
	v_add_f32_e32 v3, v12, v12
	v_add_u32_e32 v2, 0x80, v2
	v_cvt_flr_i32_f32_e32 v3, v3
	v_min_u32_e32 v2, 0xff, v2
	v_cndmask_b32_e64 v2, v2, v226, s[4:5]
	v_lshl_add_u32 v2, v2, 2, s6
	ds_add_u32 v2, v223
	v_max_i32_e32 v2, 0xffffff80, v3
	s_waitcnt vmcnt(11)
	v_add_f32_e32 v3, v13, v13
	v_add_u32_e32 v2, 0x80, v2
	v_cvt_flr_i32_f32_e32 v3, v3
	v_min_u32_e32 v2, 0xff, v2
	v_cndmask_b32_e64 v2, v2, v226, s[10:11]
	v_lshl_add_u32 v2, v2, 2, s6
	ds_add_u32 v2, v223
	v_max_i32_e32 v2, 0xffffff80, v3
	s_waitcnt vmcnt(10)
	v_add_f32_e32 v3, v14, v14
	v_add_u32_e32 v2, 0x80, v2
	v_cvt_flr_i32_f32_e32 v3, v3
	v_min_u32_e32 v2, 0xff, v2
	v_cndmask_b32_e64 v2, v2, v226, s[12:13]
	v_lshl_add_u32 v2, v2, 2, s6
	ds_add_u32 v2, v223
	v_max_i32_e32 v2, 0xffffff80, v3
	s_waitcnt vmcnt(9)
	v_add_f32_e32 v3, v15, v15
	v_add_u32_e32 v2, 0x80, v2
	v_cvt_flr_i32_f32_e32 v3, v3
	v_min_u32_e32 v2, 0xff, v2
	v_cndmask_b32_e64 v2, v2, v226, s[14:15]
	v_lshl_add_u32 v2, v2, 2, s6
	ds_add_u32 v2, v223
	v_max_i32_e32 v2, 0xffffff80, v3
	s_waitcnt vmcnt(8)
	v_add_f32_e32 v3, v16, v16
	v_add_u32_e32 v2, 0x80, v2
	v_cvt_flr_i32_f32_e32 v3, v3
	v_min_u32_e32 v2, 0xff, v2
	v_cndmask_b32_e64 v2, v2, v226, s[16:17]
	v_lshl_add_u32 v2, v2, 2, s6
	ds_add_u32 v2, v223
	v_max_i32_e32 v2, 0xffffff80, v3
	s_waitcnt vmcnt(7)
	v_add_f32_e32 v3, v17, v17
	v_add_u32_e32 v2, 0x80, v2
	v_cvt_flr_i32_f32_e32 v3, v3
	v_min_u32_e32 v2, 0xff, v2
	v_cndmask_b32_e64 v2, v2, v226, s[18:19]
	v_lshl_add_u32 v2, v2, 2, s6
	ds_add_u32 v2, v223
	v_max_i32_e32 v2, 0xffffff80, v3
	s_waitcnt vmcnt(6)
	v_add_f32_e32 v3, v18, v18
	v_add_u32_e32 v2, 0x80, v2
	v_cvt_flr_i32_f32_e32 v3, v3
	v_min_u32_e32 v2, 0xff, v2
	v_cndmask_b32_e64 v2, v2, v226, s[52:53]
	v_lshl_add_u32 v2, v2, 2, s6
	ds_add_u32 v2, v223
	v_max_i32_e32 v2, 0xffffff80, v3
	s_waitcnt vmcnt(5)
	v_add_f32_e32 v3, v19, v19
	v_add_u32_e32 v2, 0x80, v2
	v_cvt_flr_i32_f32_e32 v3, v3
	v_min_u32_e32 v2, 0xff, v2
	v_cndmask_b32_e64 v2, v2, v226, s[54:55]
	v_lshl_add_u32 v2, v2, 2, s6
	ds_add_u32 v2, v223
	v_max_i32_e32 v2, 0xffffff80, v3
	s_waitcnt vmcnt(4)
	v_add_f32_e32 v3, v20, v20
	v_add_u32_e32 v2, 0x80, v2
	v_cvt_flr_i32_f32_e32 v3, v3
	v_min_u32_e32 v2, 0xff, v2
	v_cndmask_b32_e64 v2, v2, v226, s[24:25]
	v_lshl_add_u32 v2, v2, 2, s6
	ds_add_u32 v2, v223
	v_max_i32_e32 v2, 0xffffff80, v3
	s_waitcnt vmcnt(3)
	v_add_f32_e32 v3, v21, v21
	v_add_u32_e32 v2, 0x80, v2
	v_cvt_flr_i32_f32_e32 v3, v3
	v_min_u32_e32 v2, 0xff, v2
	v_cndmask_b32_e64 v2, v2, v226, s[26:27]
	v_lshl_add_u32 v2, v2, 2, s6
	ds_add_u32 v2, v223
	v_max_i32_e32 v2, 0xffffff80, v3
	s_waitcnt vmcnt(2)
	v_add_f32_e32 v3, v22, v22
	v_add_u32_e32 v2, 0x80, v2
	v_cvt_flr_i32_f32_e32 v3, v3
	v_min_u32_e32 v2, 0xff, v2
	v_cndmask_b32_e64 v2, v2, v226, s[28:29]
	v_lshl_add_u32 v2, v2, 2, s6
	ds_add_u32 v2, v223
	v_max_i32_e32 v2, 0xffffff80, v3
	s_waitcnt vmcnt(1)
	v_add_f32_e32 v3, v23, v23
	v_add_u32_e32 v2, 0x80, v2
	v_cvt_flr_i32_f32_e32 v3, v3
	v_min_u32_e32 v2, 0xff, v2
	v_cndmask_b32_e64 v2, v2, v226, s[30:31]
	v_lshl_add_u32 v2, v2, 2, s6
	ds_add_u32 v2, v223
	v_max_i32_e32 v2, 0xffffff80, v3
	s_waitcnt vmcnt(0)
	v_add_f32_e32 v3, v24, v24
	v_add_u32_e32 v2, 0x80, v2
	v_cvt_flr_i32_f32_e32 v3, v3
	v_min_u32_e32 v2, 0xff, v2
	v_cndmask_b32_e64 v2, v2, v226, s[34:35]
	v_lshl_add_u32 v2, v2, 2, s6
	ds_add_u32 v2, v223
	v_max_i32_e32 v2, 0xffffff80, v3
	v_add_u32_e32 v2, 0x80, v2
	v_min_u32_e32 v2, 0xff, v2
	v_cndmask_b32_e64 v2, v2, v226, s[36:37]
	v_lshl_add_u32 v2, v2, 2, s6
	ds_add_u32 v2, v223
	s_waitcnt lgkmcnt(0)
	ds_read_b128 v[2:5], v7
	v_readlane_b32 s8, v254, 12
	v_readlane_b32 s9, v254, 13
	s_waitcnt lgkmcnt(0)
	v_add_u32_e32 v26, v2, v3
	v_add3_u32 v27, v26, v4, v5
	v_mov_b32_e32 v26, v27
	s_nop 1
	v_add_u32_dpp v26, v26, v26 row_shr:1 row_mask:0xf bank_mask:0xf bound_ctrl:0
	s_nop 1
	v_add_u32_dpp v26, v26, v26 row_shr:2 row_mask:0xf bank_mask:0xf bound_ctrl:0
	s_nop 1
	v_add_u32_dpp v26, v26, v26 row_shr:4 row_mask:0xf bank_mask:0xf bound_ctrl:0
	s_nop 1
	v_add_u32_dpp v26, v26, v26 row_shr:8 row_mask:0xf bank_mask:0xf bound_ctrl:0
	s_nop 1
	v_add_u32_dpp v26, v26, v26 row_bcast:15 row_mask:0xa bank_mask:0xf
	s_nop 1
	v_add_u32_dpp v26, v26, v26 row_bcast:31 row_mask:0xc bank_mask:0xf
	s_nop 1
	v_readlane_b32 s8, v26, 63
	s_nop 1
	v_sub_u32_e32 v28, s8, v26
	v_add_u32_e32 v26, v28, v27
	v_mov_b32_e32 v27, v28
	v_add_u32_e32 v30, v27, v5
	v_cmp_gt_u32_e32 vcc, s63, v30
	v_mov_b32_e32 v28, 3
	v_mov_b32_e32 v29, v27
	s_and_saveexec_b64 s[8:9], vcc
	s_mov_b32 s88, 0xefa18f08
	s_cbranch_execz .LBB0_658
	v_add_u32_e32 v5, v30, v4
	v_cmp_gt_u32_e32 vcc, s63, v5
	v_mov_b32_e32 v28, 2
	s_and_saveexec_b64 s[38:39], vcc
	v_add_u32_e32 v4, v5, v3
	s_movk_i32 s40, 0xff
	v_cmp_lt_u32_e32 vcc, s40, v4
	s_nop 1
	v_cndmask_b32_e64 v28, 0, 1, vcc
	v_cndmask_b32_e32 v30, v4, v5, vcc
	v_cndmask_b32_e32 v4, v2, v3, vcc
	s_or_b64 exec, exec, s[38:39]
	v_mov_b32_e32 v5, v4
	v_mov_b32_e32 v29, v30

; #define LAS __attribute__((address_space(3)))
; #define GAS __attribute__((address_space(1)))
; __device__ __forceinline__ unsigned skey_of(float f) { const unsigned u = __float_as_uint(f); return u ^ ((unsigned)((int)u >> 31) | 0x80000000u); }
; template <int NJ>
; __device__ __forceinline__ void select_rows(const GAS float* sr0, GAS unsigned long long* mb0, LAS unsigned* hist, LAS unsigned* kbuf, int ntl, int lane) {
;     ...
;     for (int rr = 0; rr < 8; ++rr) {
;         const GAS float* srow = sr0 + (size_t)rr * SEQ;
;         float fv[NJ];
; #pragma unroll
;         for (int j = 0; j < NJ; ++j) fv[j] = srow[64 * j];
;         { unsigned z = 0u; asm volatile("" : "+v"(z));
;           *(LAS u32x4*)(hist + 4 * lane) = (u32x4){z, z, z, z}; if (lane < 2) hist[256 + lane] = z; }
;         __builtin_amdgcn_wave_barrier();
;         unsigned key[NJ];
; #pragma unroll
;         for (int j = 0; j < NJ; ++j) {
;             const float f = fv[j]; const bool ok = (vm >> j) & 1u;
;             key[j] = ok ? skey_of(f) : 0u;
;             const int bk = min(max((int)floorf(f + f) + 128, 0), 255);
;             __hip_atomic_fetch_add(hist + (ok ? bk : 256), 1u, __ATOMIC_RELAXED, __HIP_MEMORY_SCOPE_WORKGROUP);
;         }
;         __builtin_amdgcn_wave_barrier();
;         asm volatile("s_waitcnt lgkmcnt(0)" ::: "memory");
;         unsigned B, rem, C;
;         {
;             const u32x4 hv = *(const LAS u32x4*)(hist + 4 * lane);
;             const unsigned s4 = hv.x + hv.y + hv.z + hv.w;
;             unsigned S = s4;
; #pragma unroll
;             for (int off = 1; off < 64; off <<= 1) { const unsigned n = __shfl_down(S, off); if (lane + off < 64) S += n; }
;             const unsigned excl = S - s4;
;             const bool mine = (excl < 256u) && (256u <= S);
;             unsigned dl, above, cnt, c = excl;
;             if (c + hv.w >= 256u) { dl = 3; above = c; cnt = hv.w; } else { c += hv.w; if (c + hv.z >= 256u) { dl = 2; above = c; cnt = hv.z; } else { c += hv.z; if (c + hv.y >= 256u) { dl = 1; above = c; cnt = hv.y; } else { c += hv.y; dl = 0; above = c; cnt = hv.x; } } }
.LBB0_739:
	s_mov_b32 s100, 0
	s_lshl_b32 s88, s7, 11
	v_lshl_add_u64 v[2:3], s[88:89], 2, v[8:9]
	global_load_dword v17, v[2:3], off
	global_load_dword v10, v[2:3], off offset:256
	global_load_dword v11, v[2:3], off offset:512
	global_load_dword v12, v[2:3], off offset:768
	global_load_dword v13, v[2:3], off offset:1024
	global_load_dword v14, v[2:3], off offset:1280
	global_load_dword v15, v[2:3], off offset:1536
	global_load_dword v16, v[2:3], off offset:1792
	v_mov_b32_e32 v2, 0
	s_nop 0
	v_mov_b32_e32 v3, v2
	v_mov_b32_e32 v4, v2
	v_mov_b32_e32 v5, v2
	ds_write_b128 v7, v[2:5]
	s_and_saveexec_b64 s[8:9], s[74:75]
	v_add_u32_e32 v3, v7, v38
	ds_write_b32 v3, v2 offset:1024
	s_or_b64 exec, exec, s[8:9]
	s_waitcnt vmcnt(7)
	v_add_f32_e32 v2, v17, v17
	v_cvt_flr_i32_f32_e32 v2, v2
	s_waitcnt vmcnt(6)
	v_add_f32_e32 v3, v10, v10
	v_cvt_flr_i32_f32_e32 v3, v3
	v_max_i32_e32 v2, 0xffffff80, v2
	v_add_u32_e32 v2, 0x80, v2
	v_min_u32_e32 v2, 0xff, v2
	v_cndmask_b32_e64 v2, v2, v226, s[0:1]
	v_lshl_add_u32 v2, v2, 2, s6
	ds_add_u32 v2, v223
	v_max_i32_e32 v2, 0xffffff80, v3
	s_waitcnt vmcnt(5)
	v_add_f32_e32 v3, v11, v11
	v_add_u32_e32 v2, 0x80, v2
	v_cvt_flr_i32_f32_e32 v3, v3
	v_min_u32_e32 v2, 0xff, v2
	v_cndmask_b32_e64 v2, v2, v226, s[2:3]
	v_lshl_add_u32 v2, v2, 2, s6
	ds_add_u32 v2, v223
	v_max_i32_e32 v2, 0xffffff80, v3
	s_waitcnt vmcnt(4)
	v_add_f32_e32 v3, v12, v12
	v_add_u32_e32 v2, 0x80, v2
	v_cvt_flr_i32_f32_e32 v3, v3
	v_min_u32_e32 v2, 0xff, v2
	v_cndmask_b32_e64 v2, v2, v226, s[4:5]
	v_lshl_add_u32 v2, v2, 2, s6
	ds_add_u32 v2, v223
	v_max_i32_e32 v2, 0xffffff80, v3
	s_waitcnt vmcnt(3)
	v_add_f32_e32 v3, v13, v13
	v_add_u32_e32 v2, 0x80, v2
	v_cvt_flr_i32_f32_e32 v3, v3
	v_min_u32_e32 v2, 0xff, v2
	v_cndmask_b32_e64 v2, v2, v226, s[10:11]
	v_lshl_add_u32 v2, v2, 2, s6
	ds_add_u32 v2, v223
	v_max_i32_e32 v2, 0xffffff80, v3
	s_waitcnt vmcnt(2)
	v_add_f32_e32 v3, v14, v14
	v_add_u32_e32 v2, 0x80, v2
	v_cvt_flr_i32_f32_e32 v3, v3
	v_min_u32_e32 v2, 0xff, v2
	v_cndmask_b32_e64 v2, v2, v226, s[12:13]
	v_lshl_add_u32 v2, v2, 2, s6
	ds_add_u32 v2, v223
	v_max_i32_e32 v2, 0xffffff80, v3
	s_waitcnt vmcnt(1)
	v_add_f32_e32 v3, v15, v15
	v_add_u32_e32 v2, 0x80, v2
	v_cvt_flr_i32_f32_e32 v3, v3
	v_min_u32_e32 v2, 0xff, v2
	v_cndmask_b32_e64 v2, v2, v226, s[14:15]
	v_lshl_add_u32 v2, v2, 2, s6
	ds_add_u32 v2, v223
	v_max_i32_e32 v2, 0xffffff80, v3
	s_waitcnt vmcnt(0)
	v_add_f32_e32 v3, v16, v16
	v_add_u32_e32 v2, 0x80, v2
	v_cvt_flr_i32_f32_e32 v3, v3
	v_min_u32_e32 v2, 0xff, v2
	v_cndmask_b32_e64 v2, v2, v226, s[16:17]
	v_lshl_add_u32 v2, v2, 2, s6
	ds_add_u32 v2, v223
	v_max_i32_e32 v2, 0xffffff80, v3
	v_add_u32_e32 v2, 0x80, v2
	v_min_u32_e32 v2, 0xff, v2
	v_cndmask_b32_e64 v2, v2, v226, s[18:19]
	v_lshl_add_u32 v2, v2, 2, s6
	ds_add_u32 v2, v223
	s_waitcnt lgkmcnt(0)
	ds_read_b128 v[2:5], v7
	v_readlane_b32 s8, v254, 12
	v_readlane_b32 s9, v254, 13
	s_waitcnt lgkmcnt(0)
	v_add_u32_e32 v18, v2, v3
	v_add3_u32 v19, v18, v4, v5
	v_mov_b32_e32 v18, v19
	s_nop 1
	v_add_u32_dpp v18, v18, v18 row_shr:1 row_mask:0xf bank_mask:0xf bound_ctrl:0
	s_nop 1
	v_add_u32_dpp v18, v18, v18 row_shr:2 row_mask:0xf bank_mask:0xf bound_ctrl:0
	s_nop 1
	v_add_u32_dpp v18, v18, v18 row_shr:4 row_mask:0xf bank_mask:0xf bound_ctrl:0
	s_nop 1
	v_add_u32_dpp v18, v18, v18 row_shr:8 row_mask:0xf bank_mask:0xf bound_ctrl:0
	s_nop 1
	v_add_u32_dpp v18, v18, v18 row_bcast:15 row_mask:0xa bank_mask:0xf
	s_nop 1
	v_add_u32_dpp v18, v18, v18 row_bcast:31 row_mask:0xc bank_mask:0xf
	s_nop 1
	v_readlane_b32 s8, v18, 63
	s_nop 1
	v_sub_u32_e32 v20, s8, v18
	v_add_u32_e32 v18, v20, v19
	v_mov_b32_e32 v19, v20
	v_add_u32_e32 v22, v19, v5
	v_cmp_gt_u32_e32 vcc, s63, v22
	v_mov_b32_e32 v20, 3
	v_mov_b32_e32 v21, v19
	s_and_saveexec_b64 s[8:9], vcc
	s_mov_b32 s88, 0xefa18f08
	s_cbranch_execz .LBB0_745
	v_add_u32_e32 v5, v22, v4
	v_cmp_gt_u32_e32 vcc, s63, v5
	v_mov_b32_e32 v20, 2
	s_and_saveexec_b64 s[48:49], vcc
	v_add_u32_e32 v4, v5, v3
	s_movk_i32 s50, 0xff
	v_cmp_lt_u32_e32 vcc, s50, v4
	s_nop 1
	v_cndmask_b32_e64 v20, 0, 1, vcc
	v_cndmask_b32_e32 v22, v4, v5, vcc
	v_cndmask_b32_e32 v4, v2, v3, vcc
	s_or_b64 exec, exec, s[48:49]
	v_mov_b32_e32 v5, v4
	v_mov_b32_e32 v21, v22
